# combo22 + P5 start: first unit's row-factor wait and compute moved behind the issue of the eight prologue DMAs (two cold round trips overlap)
# baseline (speedup 1.0000x reference)
.LBB0_1727:
	s_add_i32 s0, s5, s0
	s_ashr_i32 s1, s0, 31
	s_lshr_b32 s1, s1, 25
	s_add_i32 s1, s0, s1
	s_ashr_i32 s4, s1, 7
	s_and_b32 s1, s1, 0xff80
	s_sub_i32 s0, s0, s1
	s_bfe_i32 s1, s0, 0x80000
	s_bfe_u32 s1, s1, 0x3000c
	s_add_i32 s1, s0, s1
	s_bfe_i32 s5, s1, 0x80000
	s_and_b32 s1, s1, 0xf8
	s_sub_i32 s0, s0, s1
	s_lshl_b32 s4, s4, 3
	s_sext_i32_i8 s0, s0
	s_sext_i32_i16 s5, s5
	s_add_i32 s28, s4, s0
	v_mov_b32_e32 v0, v252
	s_movk_i32 s0, 0x100
	s_lshr_b32 s12, s5, 3
	s_nop 0
	v_cmp_gt_i32_e32 vcc, s0, v0
	s_and_saveexec_b64 s[8:9], vcc
	s_cbranch_execz .LBB0_1729
	v_mov_b32_e32 v180, v252
	v_lshl_add_u32 v184, s28, 8, v180
	v_ashrrev_i32_e32 v185, 31, v184
	v_lshlrev_b64 v[184:185], 6, v[184:185]
	v_lshl_add_u64 v[218:219], s[6:7], 0, v[184:185]
	v_lshl_add_u64 v[216:217], s[42:43], 0, v[184:185]
	global_load_dwordx4 v[184:187], v[218:219], off
	global_load_dwordx4 v[188:191], v[218:219], off offset:16
	global_load_dwordx4 v[192:195], v[218:219], off offset:32
	global_load_dwordx4 v[196:199], v[218:219], off offset:48
	global_load_dwordx4 v[200:203], v[216:217], off
	global_load_dwordx4 v[204:207], v[216:217], off offset:16
	global_load_dwordx4 v[208:211], v[216:217], off offset:32
	global_load_dwordx4 v[212:215], v[216:217], off offset:48
.LBB0_1729:
	s_or_b64 exec, exec, s[8:9]
	v_mov_b32_e32 v0, s12
	v_bfe_i32 v3, v2, 27, 1
	v_readfirstlane_b32 s44, v0
	v_lshlrev_b32_e32 v0, 4, v2
	v_lshrrev_b32_e32 v3, 22, v3
	v_add_u32_e32 v3, v0, v3
	v_and_b32_e32 v3, 0xfffffc00, v3
	v_sub_u32_e32 v3, v0, v3
	v_lshrrev_b32_e32 v4, 4, v3
	v_bitop3_b32 v3, v4, v3, 32 bitop3:0x6c
	v_ashrrev_i32_e32 v1, 31, v2
	v_ashrrev_i32_e32 v5, 31, v3
	v_lshrrev_b32_e32 v1, 26, v1
	v_lshrrev_b32_e32 v5, 26, v5
	v_add_u32_e32 v1, v2, v1
	v_add_u32_e32 v5, v3, v5
	v_ashrrev_i32_e32 v1, 6, v1
	v_lshrrev_b32_e32 v6, 6, v5
	v_and_b32_e32 v5, 0xc0, v5
	v_lshlrev_b32_e32 v4, 3, v1
	v_lshlrev_b32_e32 v1, 5, v1
	v_sub_u32_e32 v3, v3, v5
	v_mov_b32_e32 v5, 1
	v_and_b32_e32 v4, 0xffff0, v4
	v_and_b32_e32 v1, 32, v1
	v_ashrrev_i16_sdwa v3, v5, sext(v3) dst_sel:DWORD dst_unused:UNUSED_PAD src0_sel:DWORD src1_sel:BYTE_0
	v_add_u32_sdwa v1, v1, sext(v3) dst_sel:DWORD dst_unused:UNUSED_PAD src0_sel:DWORD src1_sel:WORD_0
	v_add_lshl_u32 v3, v6, v4, 12
	v_add_u32_e32 v0, 0x2000, v0
	v_lshl_add_u32 v254, v1, 1, v3
	v_ashrrev_i32_e32 v1, 31, v0
	v_lshrrev_b32_e32 v1, 22, v1
	v_add_u32_e32 v1, v0, v1
	v_ashrrev_i32_e32 v1, 10, v1
	v_mul_i32_i24_e32 v3, 0x400, v1
	v_sub_u32_e32 v0, v0, v3
	v_lshrrev_b32_e32 v3, 4, v0
	s_ashr_i32 s29, s28, 31
	v_bitop3_b32 v0, v3, v0, 32 bitop3:0x6c
	s_lshl_b64 s[0:1], s[28:29], 20
	v_ashrrev_i32_e32 v4, 31, v0
	s_add_u32 s4, s40, s0
	s_mov_b32 s45, 0
	v_lshrrev_b32_e32 v4, 26, v4
	s_addc_u32 s5, s41, s1
	s_bfe_i64 s[0:1], s[44:45], 0x80000
	v_add_u32_e32 v4, v0, v4
	s_lshl_b64 s[0:1], s[0:1], 20
	v_readlane_b32 s8, v255, 6
	v_lshrrev_b32_e32 v6, 6, v4
	v_and_b32_e32 v4, 0xc0, v4
	v_readlane_b32 s9, v255, 7
	s_add_u32 s30, s8, s0
	v_lshlrev_b32_e32 v3, 3, v1
	v_lshlrev_b32_e32 v1, 5, v1
	v_sub_u32_e32 v0, v0, v4
	s_addc_u32 s31, s9, s1
	v_and_b32_e32 v3, 0xffff0, v3
	v_and_b32_e32 v1, 32, v1
	v_ashrrev_i16_sdwa v0, v5, sext(v0) dst_sel:DWORD dst_unused:UNUSED_PAD src0_sel:DWORD src1_sel:BYTE_0
	s_ashr_i32 s1, s14, 6
	v_add_u32_sdwa v0, v1, sext(v0) dst_sel:DWORD dst_unused:UNUSED_PAD src0_sel:DWORD src1_sel:WORD_0
	v_add_lshl_u32 v1, v6, v3, 12
	s_lshl_b32 s33, s1, 10
	v_lshl_add_u32 v223, v0, 1, v1
	s_add_i32 s34, s33, 0
	v_mov_b32_e32 v0, v254
	s_add_i32 m0, s34, 0x10000
	s_ashr_i32 s0, s14, 8
	global_load_lds_dwordx4 v0, s[30:31]
	v_mov_b32_e32 v0, v223
	s_add_i32 m0, s34, 0x12000
	s_add_u32 s8, s30, 0x80000
	global_load_lds_dwordx4 v0, s[30:31]
	v_mov_b32_e32 v0, v254
	s_addc_u32 s9, s31, 0
	s_add_i32 m0, s34, 0x14000
	s_add_i32 s35, s34, 0x2000
	global_load_lds_dwordx4 v0, s[8:9]
	v_mov_b32_e32 v0, v223
	s_add_i32 m0, s34, 0x16000
	v_mov_b32_e32 v1, 0
	global_load_lds_dwordx4 v0, s[8:9]
	v_mov_b32_e32 v0, v254
	s_mov_b32 m0, s34
	s_add_u32 s8, s4, 0x80000
	global_load_lds_dwordx4 v0, s[4:5]
	v_mov_b32_e32 v0, v223
	s_mov_b32 m0, s35
	s_addc_u32 s9, s5, 0
	global_load_lds_dwordx4 v0, s[4:5]
	s_add_i32 s38, s34, 0x4000
	v_mov_b32_e32 v0, v254
	s_mov_b32 m0, s38
	s_add_i32 s39, s34, 0x6000
	global_load_lds_dwordx4 v0, s[8:9]
	v_mov_b32_e32 v0, v223
	s_mov_b32 m0, s39
	s_cmp_eq_u32 s0, 1
	global_load_lds_dwordx4 v0, s[8:9]
	s_cselect_b64 s[8:9], -1, 0
	s_movk_i32 s20, 0x100
	v_cmp_gt_i32_e32 vcc, s20, v252
	s_and_saveexec_b64 s[46:47], vcc
	s_cbranch_execz .Lp5b0_skip
	v_mov_b32_e32 v181, 0x358637bd
	s_mov_b32 s20, 0xf800000
	v_mov_b32_e32 v183, 0x260
	s_mov_b32 s10, 0x42000000
	s_mov_b32 s11, 0x41000000
	s_waitcnt vmcnt(8)
	v_pk_add_f32 v[186:187], v[186:187], v[190:191]
	v_pk_add_f32 v[184:185], v[184:185], v[188:189]
	v_pk_add_f32 v[188:189], v[194:195], v[198:199]
	v_pk_add_f32 v[190:191], v[192:193], v[196:197]
	v_pk_add_f32 v[192:193], v[202:203], v[206:207]
	v_pk_add_f32 v[194:195], v[200:201], v[204:205]
	v_pk_add_f32 v[196:197], v[210:211], v[214:215]
	v_pk_add_f32 v[198:199], v[208:209], v[212:213]
	v_pk_add_f32 v[186:187], v[186:187], v[188:189]
	v_pk_add_f32 v[184:185], v[184:185], v[190:191]
	v_pk_add_f32 v[188:189], v[192:193], v[196:197]
	v_pk_add_f32 v[190:191], v[194:195], v[198:199]
	s_nop 0
	v_pk_mov_b32 v[192:193], v[190:191], v[188:189] op_sel:[1,0]
	v_mov_b32_e32 v191, v189
	v_pk_mov_b32 v[188:189], v[184:185], v[186:187] op_sel:[1,0]
	v_mov_b32_e32 v185, v187
	v_pk_add_f32 v[186:187], v[192:193], v[190:191]
	v_pk_add_f32 v[184:185], v[188:189], v[184:185]
	v_add_f32_e32 v186, v186, v187
	v_add_f32_e32 v184, v184, v185
	v_fmamk_f32 v185, v186, 0x3a000000, v181
	v_fmac_f32_e32 v181, 0x3a000000, v184
	v_mul_f32_e32 v184, 0x4f800000, v185
	v_cmp_gt_f32_e32 vcc, s20, v185
	v_mul_f32_e32 v186, 0x4f800000, v181
	v_cmp_gt_f32_e64 s[20:21], s20, v181
	v_cndmask_b32_e32 v184, v185, v184, vcc
	v_sqrt_f32_e32 v185, v184
	v_cndmask_b32_e64 v181, v181, v186, s[20:21]
	v_sqrt_f32_e32 v186, v181
	v_lshl_add_u32 v187, v180, 3, 0
	v_add_u32_e32 v180, -1, v185
	v_fma_f32 v191, -v180, v185, v184
	v_add_u32_e32 v189, -1, v186
	v_add_u32_e32 v188, 1, v185
	v_fma_f32 v193, -v189, v186, v181
	v_cmp_ge_f32_e64 s[22:23], 0, v191
	v_add_u32_e32 v190, 1, v186
	v_fma_f32 v192, -v188, v185, v184
	v_cndmask_b32_e64 v180, v185, v180, s[22:23]
	v_cmp_ge_f32_e64 s[22:23], 0, v193
	v_fma_f32 v194, -v190, v186, v181
	s_nop 0
	v_cndmask_b32_e64 v185, v186, v189, s[22:23]
	v_cmp_lt_f32_e64 s[22:23], 0, v192
	s_nop 1
	v_cndmask_b32_e64 v180, v180, v188, s[22:23]
	v_cmp_lt_f32_e64 s[22:23], 0, v194
	v_mul_f32_e32 v186, 0x37800000, v180
	v_cndmask_b32_e32 v180, v180, v186, vcc
	v_cndmask_b32_e64 v185, v185, v190, s[22:23]
	v_mul_f32_e32 v188, 0x37800000, v185
	v_cmp_class_f32_e32 vcc, v184, v183
	v_cndmask_b32_e64 v185, v185, v188, s[20:21]
	s_nop 0
	v_cndmask_b32_e32 v180, v180, v184, vcc
	v_cmp_class_f32_e32 vcc, v181, v183
	s_nop 1
	v_cndmask_b32_e32 v181, v185, v181, vcc
	v_div_scale_f32 v183, s[20:21], v181, v181, 1.0
	v_div_scale_f32 v185, s[20:21], v180, v180, 1.0
	v_rcp_f32_e32 v186, v183
	v_rcp_f32_e32 v188, v185
	v_div_scale_f32 v184, vcc, 1.0, v181, 1.0
	v_fma_f32 v190, -v183, v186, 1.0
	v_fma_f32 v191, -v185, v188, 1.0
	v_fmac_f32_e32 v186, v190, v186
	v_div_scale_f32 v189, s[20:21], 1.0, v180, 1.0
	v_fmac_f32_e32 v188, v191, v188
	v_mul_f32_e32 v190, v184, v186
	v_mul_f32_e32 v191, v189, v188
	v_fma_f32 v192, -v183, v190, v184
	v_fma_f32 v193, -v185, v191, v189
	v_fmac_f32_e32 v190, v192, v186
	v_fmac_f32_e32 v191, v193, v188
	v_fma_f32 v183, -v183, v190, v184
	v_fma_f32 v184, -v185, v191, v189
	v_div_fmas_f32 v183, v183, v186, v190
	s_mov_b64 vcc, s[20:21]
	v_div_fixup_f32 v181, v183, v181, 1.0
	v_div_fmas_f32 v183, v184, v188, v191
	v_div_fixup_f32 v180, v183, v180, 1.0
	v_pk_mul_f32 v[184:185], v[180:181], s[10:11]
	v_mul_f32_e32 v181, 0x39000000, v181
	v_div_scale_f32 v180, s[20:21], v185, v185, v184
	v_rcp_f32_e32 v183, v180
	v_div_scale_f32 v186, vcc, v184, v185, v184
	v_fma_f32 v188, -v180, v183, 1.0
	v_fmac_f32_e32 v183, v188, v183
	v_mul_f32_e32 v188, v186, v183
	v_fma_f32 v189, -v180, v188, v186
	v_fmac_f32_e32 v188, v189, v183
	v_fma_f32 v180, -v180, v188, v186
	v_div_fmas_f32 v180, v180, v183, v188
	v_div_fixup_f32 v180, v180, v185, v184
	v_add_u32_e32 v183, 0x20000, v187
	ds_write_b64 v183, v[180:181]
.Lp5b0_skip:
	s_or_b64 exec, exec, s[46:47]
	s_cmp_lg_u32 s0, 1
	s_cbranch_scc1 .LBB0_1731
	s_barrier
